# MLA latent tile loop back-edge rotation: running-max copy and next tile K address computed before the loop-back barrier
# speedup vs baseline: 1.0011x; 1.0011x over previous
; template <int DQK, int KSB>
; __device__ __forceinline__ void attn_scores(LAS const unsigned char* Kt, const bf16x8 (&qf)[DQK / 16], f32x16 (&p)[2], int r32, int hi) {
;     constexpr int NK = DQK / 16;
;     LAS const unsigned char* kp = Kt + r32 * KSB + hi * 16;
;     f32x16 p0, p1;
; #pragma unroll
;     for (int e = 0; e < 16; ++e) { p0[e] = 0.f; p1[e] = 0.f; }
;     bf16x8 kr[3][2];
;     ...
;     QK_LOAD(0); QK_LOAD(1); SCHED_FENCE();
; #pragma unroll
;     for (int ks = 0; ks < NK; ++ks) {
;         if (ks + 2 < NK) QK_LOAD(ks + 2);
;         p0 = MFMA32(kr[ks % 3][0], qf[ks], p0); p1 = MFMA32(kr[ks % 3][1], qf[ks], p1); SCHED_FENCE();
;     }
;     ...
;     p[0] = p0; p[1] = p1;
; }
; template <int DV, bool MASK>
; __device__ __forceinline__ void attn_softmax(f32x16 (&p)[2], f32x16 (&o)[DV / 32], float& m, float& l, float cs, int hi, int dq) {
;     if (MASK) { if (__builtin_amdgcn_readfirstlane(dq) != NO_MASK) {
; #pragma unroll
;         for (int kvb = 0; kvb < 2; ++kvb)
; #pragma unroll
;             for (int e = 0; e < 16; ++e) { const int rel = dq + 32 * kvb + (e & 3) + 8 * (e >> 2) + 4 * hi; if (rel > 128 || rel < -128) p[kvb][e] = -INFINITY; } } }
;     float mx;
;     {
;         float a0 = fmaxf(fmaxf(p[0][0], p[0][1]), p[0][2]), a1 = fmaxf(fmaxf(p[0][8], p[0][9]), p[0][10]), a2 = fmaxf(fmaxf(p[1][0], p[1][1]), p[1][2]), a3 = fmaxf(fmaxf(p[1][8], p[1][9]), p[1][10]);
;         a0 = fmaxf(fmaxf(a0, p[0][3]), p[0][4]); a1 = fmaxf(fmaxf(a1, p[0][11]), p[0][12]); a2 = fmaxf(fmaxf(a2, p[1][3]), p[1][4]); a3 = fmaxf(fmaxf(a3, p[1][11]), p[1][12]);
;         a0 = fmaxf(fmaxf(a0, p[0][5]), p[0][6]); a1 = fmaxf(fmaxf(a1, p[0][13]), p[0][14]); a2 = fmaxf(fmaxf(a2, p[1][5]), p[1][6]); a3 = fmaxf(fmaxf(a3, p[1][13]), p[1][14]);
;         a0 = fmaxf(a0, p[0][7]); a1 = fmaxf(a1, p[0][15]); a2 = fmaxf(a2, p[1][7]); a3 = fmaxf(a3, p[1][15]);
;         mx = fmaxf(fmaxf(a0, a1), fmaxf(a2, a3));
;         const auto rr = __builtin_amdgcn_permlane32_swap(__float_as_uint(mx), __float_as_uint(mx), false, false);
;         mx = fmaxf(__uint_as_float(rr[0]), __uint_as_float(rr[1])); }
;     const float mn = fmaxf(m, mx * cs);
;     if (__any(mn - m > ATT_THR)) {
;         const float alpha = fexp2(m - mn); m = mn; l *= alpha;
; #pragma unroll
;         for (int d = 0; d < DV / 32; ++d)
; #pragma unroll
;             for (int e = 0; e < 16; ++e) o[d][e] *= alpha;
.Lmla_x_entry:
	ds_read_b128 v[34:37], v32
	ds_read_b128 v[38:41], v32 offset:32
	ds_read_b128 v[42:45], v32 offset:12800
	ds_read_b128 v[210:213], v32 offset:12832
	s_waitcnt lgkmcnt(3)
	v_mfma_f32_32x32x16_bf16 v[112:127], v[34:37], v[18:21], 0
	ds_read_b128 v[34:37], v32 offset:64
	ds_read_b128 v[214:217], v32 offset:12864
	s_waitcnt lgkmcnt(3)
	v_mfma_f32_32x32x16_bf16 v[96:111], v[42:45], v[18:21], 0
	v_mfma_f32_32x32x16_bf16 v[112:127], v[38:41], v[22:25], v[112:127]
	ds_read_b128 v[38:41], v32 offset:96
	ds_read_b128 v[42:45], v32 offset:12896
	s_waitcnt lgkmcnt(4)
	v_mfma_f32_32x32x16_bf16 v[96:111], v[210:213], v[22:25], v[96:111]
	s_waitcnt lgkmcnt(3)
	v_mfma_f32_32x32x16_bf16 v[112:127], v[34:37], v[26:29], v[112:127]
	ds_read_b128 v[34:37], v32 offset:128
	ds_read_b128 v[210:213], v32 offset:12928
	s_waitcnt lgkmcnt(4)
	v_mfma_f32_32x32x16_bf16 v[96:111], v[214:217], v[26:29], v[96:111]
	s_waitcnt lgkmcnt(3)
	v_mfma_f32_32x32x16_bf16 v[112:127], v[38:41], v[128:131], v[112:127]
	ds_read_b128 v[38:41], v32 offset:160
	ds_read_b128 v[214:217], v32 offset:12960
	s_waitcnt lgkmcnt(4)
	v_mfma_f32_32x32x16_bf16 v[96:111], v[42:45], v[128:131], v[96:111]
	s_waitcnt lgkmcnt(3)
	v_mfma_f32_32x32x16_bf16 v[112:127], v[34:37], v[132:135], v[112:127]
	ds_read_b128 v[34:37], v32 offset:192
	ds_read_b128 v[42:45], v32 offset:12992
	s_waitcnt lgkmcnt(4)
	v_mfma_f32_32x32x16_bf16 v[96:111], v[210:213], v[132:135], v[96:111]
	s_waitcnt lgkmcnt(3)
	v_mfma_f32_32x32x16_bf16 v[112:127], v[38:41], v[136:139], v[112:127]
	ds_read_b128 v[38:41], v32 offset:224
	ds_read_b128 v[210:213], v32 offset:13024
	s_waitcnt lgkmcnt(4)
	v_mfma_f32_32x32x16_bf16 v[96:111], v[214:217], v[136:139], v[96:111]
	s_waitcnt lgkmcnt(3)
	v_mfma_f32_32x32x16_bf16 v[112:127], v[34:37], v[140:143], v[112:127]
	ds_read_b128 v[34:37], v32 offset:256
	ds_read_b128 v[214:217], v32 offset:13056
	s_waitcnt lgkmcnt(4)
	v_mfma_f32_32x32x16_bf16 v[96:111], v[42:45], v[140:143], v[96:111]
	s_waitcnt lgkmcnt(3)
	v_mfma_f32_32x32x16_bf16 v[112:127], v[38:41], v[144:147], v[112:127]
	ds_read_b128 v[38:41], v32 offset:288
	ds_read_b128 v[42:45], v32 offset:13088
	s_waitcnt lgkmcnt(4)
	v_mfma_f32_32x32x16_bf16 v[96:111], v[210:213], v[144:147], v[96:111]
	s_waitcnt lgkmcnt(3)
	v_mfma_f32_32x32x16_bf16 v[112:127], v[34:37], v[152:155], v[112:127]
	ds_read_b128 v[34:37], v32 offset:320
	ds_read_b128 v[210:213], v32 offset:13120
	s_waitcnt lgkmcnt(4)
	v_mfma_f32_32x32x16_bf16 v[96:111], v[214:217], v[152:155], v[96:111]
	s_waitcnt lgkmcnt(3)
	v_mfma_f32_32x32x16_bf16 v[112:127], v[38:41], v[148:151], v[112:127]
	ds_read_b128 v[38:41], v32 offset:352
	ds_read_b128 v[214:217], v32 offset:13152
	s_waitcnt lgkmcnt(4)
	v_mfma_f32_32x32x16_bf16 v[96:111], v[42:45], v[148:151], v[96:111]
	s_waitcnt lgkmcnt(3)
	v_mfma_f32_32x32x16_bf16 v[112:127], v[34:37], v[160:163], v[112:127]
	s_waitcnt lgkmcnt(2)
	v_mfma_f32_32x32x16_bf16 v[96:111], v[210:213], v[160:163], v[96:111]
	s_waitcnt lgkmcnt(1)
	v_mfma_f32_32x32x16_bf16 v[112:127], v[38:41], v[156:159], v[112:127]
	s_waitcnt lgkmcnt(0)
	v_mfma_f32_32x32x16_bf16 v[96:111], v[214:217], v[156:159], v[96:111]
	s_nop 9
	v_max_f32_e32 v32, v113, v113
	v_max_f32_e32 v34, v112, v112
	v_max_f32_e32 v36, v105, v105
	v_max_f32_e32 v37, v104, v104
	v_max_f32_e32 v32, v34, v32
	v_max_f32_e32 v34, v121, v121
	v_max_f32_e32 v35, v120, v120
	v_max_f32_e32 v36, v37, v36
	v_max_f32_e32 v34, v35, v34
	v_max3_f32 v35, v96, v97, v98
	v_max3_f32 v36, v36, v106, v107
	v_max3_f32 v32, v32, v114, v115
	v_max3_f32 v34, v34, v122, v123
	v_max3_f32 v35, v35, v99, v100
	v_max3_f32 v36, v36, v108, v109
	v_max3_f32 v32, v32, v116, v117
	v_max3_f32 v34, v34, v124, v125
	v_max3_f32 v35, v35, v101, v102
	v_max3_f32 v36, v36, v110, v111
	v_max3_f32 v32, v32, v118, v119
	v_max3_f32 v34, v34, v126, v127
	v_max3_f32 v35, v35, v103, v36
	v_max3_f32 v32, v32, v34, v35
	v_mov_b32_e32 v34, v32
	s_nop 1
	v_permlane32_swap_b32_e32 v32, v34
	v_max_f32_e32 v34, v34, v34
	v_max_f32_e32 v32, v32, v32
	v_max_f32_e32 v32, v32, v34
	v_mul_f32_e32 v32, 0x3dd53b94, v32
	v_max_f32_e32 v34, v208, v208
	v_max_f32_e32 v32, v34, v32
	v_sub_f32_e32 v34, v32, v208
	v_cmp_lt_f32_e32 vcc, s34, v34
	s_barrier
	s_cbranch_vccz .LBB0_972
	v_sub_f32_e32 v34, v208, v32
	v_exp_f32_e32 v34, v34
	s_nop 0
	v_mul_f32_e32 v201, v201, v34
	v_pk_mul_f32 v[94:95], v[94:95], v[34:35] op_sel_hi:[1,0]
	v_pk_mul_f32 v[92:93], v[92:93], v[34:35] op_sel_hi:[1,0]
	v_pk_mul_f32 v[90:91], v[90:91], v[34:35] op_sel_hi:[1,0]
	v_pk_mul_f32 v[88:89], v[88:89], v[34:35] op_sel_hi:[1,0]
	v_pk_mul_f32 v[86:87], v[86:87], v[34:35] op_sel_hi:[1,0]
	v_pk_mul_f32 v[84:85], v[84:85], v[34:35] op_sel_hi:[1,0]
	v_pk_mul_f32 v[82:83], v[82:83], v[34:35] op_sel_hi:[1,0]
	v_pk_mul_f32 v[80:81], v[80:81], v[34:35] op_sel_hi:[1,0]
	v_pk_mul_f32 v[78:79], v[78:79], v[34:35] op_sel_hi:[1,0]
	v_pk_mul_f32 v[76:77], v[76:77], v[34:35] op_sel_hi:[1,0]
	v_pk_mul_f32 v[74:75], v[74:75], v[34:35] op_sel_hi:[1,0]
	v_pk_mul_f32 v[72:73], v[72:73], v[34:35] op_sel_hi:[1,0]
	v_pk_mul_f32 v[70:71], v[70:71], v[34:35] op_sel_hi:[1,0]
	v_pk_mul_f32 v[68:69], v[68:69], v[34:35] op_sel_hi:[1,0]
	v_pk_mul_f32 v[66:67], v[66:67], v[34:35] op_sel_hi:[1,0]
	v_pk_mul_f32 v[64:65], v[64:65], v[34:35] op_sel_hi:[1,0]
	v_pk_mul_f32 v[62:63], v[62:63], v[34:35] op_sel_hi:[1,0]
	v_pk_mul_f32 v[60:61], v[60:61], v[34:35] op_sel_hi:[1,0]
	v_pk_mul_f32 v[58:59], v[58:59], v[34:35] op_sel_hi:[1,0]
	v_pk_mul_f32 v[56:57], v[56:57], v[34:35] op_sel_hi:[1,0]
	v_pk_mul_f32 v[54:55], v[54:55], v[34:35] op_sel_hi:[1,0]
	v_pk_mul_f32 v[52:53], v[52:53], v[34:35] op_sel_hi:[1,0]
	v_pk_mul_f32 v[50:51], v[50:51], v[34:35] op_sel_hi:[1,0]
	v_pk_mul_f32 v[48:49], v[48:49], v[34:35] op_sel_hi:[1,0]
	v_pk_mul_f32 v[16:17], v[16:17], v[34:35] op_sel_hi:[1,0]
	v_pk_mul_f32 v[14:15], v[14:15], v[34:35] op_sel_hi:[1,0]
	v_pk_mul_f32 v[12:13], v[12:13], v[34:35] op_sel_hi:[1,0]
	v_pk_mul_f32 v[10:11], v[10:11], v[34:35] op_sel_hi:[1,0]
	v_pk_mul_f32 v[8:9], v[8:9], v[34:35] op_sel_hi:[1,0]
	v_pk_mul_f32 v[6:7], v[6:7], v[34:35] op_sel_hi:[1,0]
	v_pk_mul_f32 v[4:5], v[4:5], v[34:35] op_sel_hi:[1,0]
	v_pk_mul_f32 v[2:3], v[2:3], v[34:35] op_sel_hi:[1,0]
	s_branch .LBB0_973

; #define LAS __attribute__((address_space(3)))
; #define MLA_LOAD(t) do { const char* kb_ = kvb0 + (size_t)(t) * (64 * 1024 * 2); const char* rb_ = krb0 + (size_t)(t) * (64 * 64 * 2); \
;         kreg[0] = *(const v4u*)(kb_ + kgo); kreg[1] = *(const v4u*)(kb_ + 32 * 1024 * 2 + kgo); kreg[2] = *(const v4u*)(rb_ + rgo); \
;         vreg[0] = *(const v4u*)(kb_ + 256 + kgo); vreg[1] = *(const v4u*)(kb_ + 32 * 1024 * 2 + 256 + kgo); } while (0)
; #define MLA_STORE(buf) do { LAS unsigned char* Kt_ = L + (buf) * MLA_BUF; LAS unsigned char* Vt_ = Kt_ + MLA_KT; \
;         *(LAS v4u*)(Kt_ + klo) = kreg[0]; *(LAS v4u*)(Kt_ + 32 * MLA_KSB + klo) = kreg[1]; *(LAS v4u*)(Kt_ + rlo) = kreg[2]; \
;         *(LAS v4u*)(Vt_ + vlo) = vreg[0]; *(LAS v4u*)(Vt_ + 32 * MLA_VRB + vlo) = vreg[1]; } while (0)
; __device__ __forceinline__ void mla_unit(const bf16* QM, const bf16* KVM, const bf16* KR, bf16* Y, int b, int h, int qrow0, int ntiles, bool latent, LAS unsigned char* L, int tid_in) {
;     ...
;     for (int t = 0; t < ntiles; ++t) {
;         LAS const unsigned char* Kt = L + bcur * MLA_BUF;
;         f32x16 p[2];
;         __builtin_amdgcn_sched_barrier(0);
;         attn_scores<192, MLA_KSB>(Kt, qf, p, r32, hi);
;         __syncthreads();
;         attn_softmax<128, false>(p, o, m, l, cs, hi, 0);
;         attn_pv<128, MLA_VRB>(Kt + MLA_KT, p, o, vtb);
;         if (t + 2 < ntiles) { MLA_STORE(bst); if (t + 3 < ntiles) MLA_LOAD(t + 3); }
;         __syncthreads();
;         bcur = bcur == 2 ? 0 : bcur + 1; bst = bst == 2 ? 0 : bst + 1;
;     }
.LBB0_976:
	s_add_i32 s12, s11, 1
	s_cmp_lg_u32 s11, 2
	s_cselect_b32 s11, s12, 0
	s_add_i32 s12, s9, 1
	s_cmp_lg_u32 s9, 2
	s_cselect_b32 s9, s12, 0
	s_add_i32 s10, s10, 1
	s_add_u32 s4, s4, 0x20000
	s_addc_u32 s5, s5, 0
	s_cmp_eq_u32 s4, 0x1080000
	v_lshl_add_u64 v[202:203], v[202:203], 0, s[62:63]
	v_mov_b32_e32 v208, v32
	s_mul_i32 s12, s11, 0xb400
	v_add3_u32 v32, s12, v207, v30
	s_waitcnt lgkmcnt(0)
	s_barrier
	s_cbranch_scc1 .LBB0_978
	s_branch .Lmla_x_entry
